# panel exchange (layer-1 out-proj and FFN-down epilogues): one counter atomic per workgroup (add 8 after a workgroup barrier) instead of one per wave
# speedup vs baseline: 1.0052x; 1.0052x over previous
;     __device__ __forceinline__ void fused(Acc& acc, const pg8::Unit& u, int wr, int wc, int fr, int fq, LAS unsigned char* lds, int wid, int lane) const {
;     ...
;         if (lane < 32) { const float tsum = (P[row * 4 + 0] + P[row * 4 + 1]) + (P[row * 4 + 2] + P[row * 4 + 3]);
;             __hip_atomic_store(slots + (size_t)(tile0 + row) * 4 + u.pn, __float_as_uint(tsum), __ATOMIC_RELAXED, __HIP_MEMORY_SCOPE_AGENT); }
;         asm volatile("s_waitcnt vmcnt(0)" ::: "memory");
;         if (lane == 0) __hip_atomic_fetch_add(cnt + 64 * u.pm, 1u, __ATOMIC_RELAXED, __HIP_MEMORY_SCOPE_AGENT);
;         if (wid == 0) {
;             unsigned sp = 0;
;             while ((unsigned)__builtin_amdgcn_readfirstlane(__hip_atomic_load(cnt + 64 * u.pm, __ATOMIC_RELAXED, __HIP_MEMORY_SCOPE_AGENT)) < 32u) { if (++sp > (1u << 20)) break; }
;             __builtin_amdgcn_fence(__ATOMIC_ACQUIRE, "agent");
;         }
.LBB0_965:
	s_or_b64 exec, exec, s[4:5]
	s_waitcnt vmcnt(0)
	s_barrier
	s_cmp_gt_u32 s20, 63
	s_cbranch_scc1 .LBB0_972
	v_cmp_eq_u32_e32 vcc, 0, v160
	s_and_saveexec_b64 s[4:5], vcc
	s_cbranch_execz .LBB0_968
	s_mov_b64 s[8:9], exec
	v_mbcnt_lo_u32_b32 v19, s8, 0
	v_mbcnt_hi_u32_b32 v19, s9, v19
	v_cmp_eq_u32_e32 vcc, 0, v19
	s_and_b64 s[10:11], exec, vcc
	s_mov_b64 exec, s[10:11]
	s_cbranch_execz .LBB0_968
	s_lshl_b32 s10, s6, 6
	s_ashr_i32 s11, s10, 31
	s_lshl_b64 s[10:11], s[10:11], 2
	v_readlane_b32 s12, v254, 14
	s_add_u32 s10, s12, s10
	v_readlane_b32 s12, v254, 15
	s_addc_u32 s11, s12, s11
	s_mov_b32 s8, 8
	v_mov_b32_e32 v19, s8
	global_atomic_add v161, v19, s[10:11]

;     __device__ __forceinline__ void fused(Acc& acc, const pg8::Unit& u, int wr, int wc, int fr, int fq, LAS unsigned char* lds, int wid, int lane) const {
;     ...
;         if (lane < 32) { const float tsum = (P[row * 4 + 0] + P[row * 4 + 1]) + (P[row * 4 + 2] + P[row * 4 + 3]);
;             __hip_atomic_store(slots + (size_t)(tile0 + row) * 4 + u.pn, __float_as_uint(tsum), __ATOMIC_RELAXED, __HIP_MEMORY_SCOPE_AGENT); }
;         asm volatile("s_waitcnt vmcnt(0)" ::: "memory");
;         if (lane == 0) __hip_atomic_fetch_add(cnt + 64 * u.pm, 1u, __ATOMIC_RELAXED, __HIP_MEMORY_SCOPE_AGENT);
;         if (wid == 0) {
;             unsigned sp = 0;
;             while ((unsigned)__builtin_amdgcn_readfirstlane(__hip_atomic_load(cnt + 64 * u.pm, __ATOMIC_RELAXED, __HIP_MEMORY_SCOPE_AGENT)) < 32u) { if (++sp > (1u << 20)) break; }
;             __builtin_amdgcn_fence(__ATOMIC_ACQUIRE, "agent");
;         }
.LBB0_1327:
	s_or_b64 exec, exec, s[6:7]
	s_waitcnt vmcnt(0)
	s_barrier
	s_cmp_gt_u32 s15, 63
	s_cbranch_scc1 .LBB0_1334
	v_cmp_eq_u32_e32 vcc, 0, v160
	s_and_saveexec_b64 s[6:7], vcc
	s_cbranch_execz .LBB0_1330
	s_mov_b64 s[8:9], exec
	v_mbcnt_lo_u32_b32 v3, s8, 0
	v_mbcnt_hi_u32_b32 v3, s9, v3
	v_cmp_eq_u32_e32 vcc, 0, v3
	s_and_b64 s[10:11], exec, vcc
	s_mov_b64 exec, s[10:11]
	s_cbranch_execz .LBB0_1330
	s_lshl_b32 s10, s38, 6
	s_ashr_i32 s11, s10, 31
	s_lshl_b64 s[10:11], s[10:11], 2
	v_readlane_b32 s12, v254, 33
	s_add_u32 s10, s12, s10
	v_readlane_b32 s12, v254, 34
	s_addc_u32 s11, s12, s11
	s_mov_b32 s8, 8
	v_mov_b32_e32 v3, s8
	global_atomic_add v161, v3, s[10:11]
